# earlypoll: deferred-transpose flag load issued at the z-unit epilogue entry so its round trip overlaps the epilogue; loop top checks that value first
# speedup vs baseline: 1.0005x; 1.0005x over previous
; #define LAS __attribute__((address_space(3)))
; __device__ __forceinline__ int lane_id() { return (int)__builtin_amdgcn_mbcnt_hi(~0u, __builtin_amdgcn_mbcnt_lo(~0u, 0u)); }
; #define PG8_BAR __builtin_amdgcn_s_barrier()
; template <class Epi, bool ALIGN_EPI>
; __device__ __forceinline__ void gemm_phase(LAS unsigned char* lds, const Gemm g, const StaticOrder& S, const Epi& E, const int wid) {
;     ...
;         if (!has_next) break;
; #pragma unroll
;         for (int a = 0; a < 2; ++a)
; #pragma unroll
;             for (int b = 0; b < 2; ++b)
; #pragma unroll
;                 for (int m = 0; m < 4; ++m)
; #pragma unroll
;                     for (int n = 0; n < 2; ++n) acc[a][b][m][n] = (f32x4){0.f, 0.f, 0.f, 0.f};
;         cur = nxt; cA = nA; cB = nB; ++ui;
;         if constexpr (ALIGN_EPI) { if (wr == 1) PG8_BAR; }
; __global__ void __launch_bounds__(NWAVES * 64, 2) fwd(Args args) {
;     ...
;         {
;             int l3 = lane_id(); asm volatile("" : "+v"(l3));
;             LAS float* scr = (LAS float*)(lds + wid * 16384);
;             constexpr int I_OUT = (DM / 64) * (DM / 32);
;             const int first = split ? 224 : 0, nw = (G - first) * NWAVES;
;             if (bx >= first)
;                 for (int it = (bx - first) * NWAVES + wid; it < 2 * I_OUT; it += nw) {
;                     if (it < I_OUT) p0_transpose_item(w_out, DM, DM, WoutT, nullptr, scr, it, l3);
;                     else p0_transpose_item(w_gate, DM, DM, WgT, ple_norm, scr, it - I_OUT, l3);
;                 }
;         }
.LBB0_102:
	s_add_i32 s59, s59, 1
	s_cmp_lt_u32 s59, 2
	s_cbranch_scc1 .Ldw_ok
	s_cmp_gt_u32 s59, 3
	s_cbranch_scc1 .Ldw_ok
	s_sub_i32 s5, s59, 1
	s_lshl_b32 s5, s5, 5
	s_waitcnt vmcnt(0)
	v_readfirstlane_b32 s4, v253
	s_cmp_ge_u32 s4, s5
	s_cbranch_scc1 .Ldw_ok

; __device__ __forceinline__ u32x4 pack8(const float (&v)[8]) { u32x4 w; w.x = cvtpk(v[0], v[1]); w.y = cvtpk(v[2], v[3]); w.z = cvtpk(v[4], v[5]); w.w = cvtpk(v[6], v[7]); return w; }
;     template <int TYPE> __device__ __forceinline__ void run(const Acc& acc, const Unit& u, int wr, int wc, int fr, int fq) const {
;     ...
;                 if (TYPE == 3) {
; #pragma unroll
;                     for (int bj = 0; bj < 2; ++bj)
; #pragma unroll
;                         for (int j = 0; j < 8; ++j) { const float x = v[bj][j]; v[bj][j] = x * __builtin_amdgcn_rcpf(1.0f + __builtin_amdgcn_exp2f(-1.4426950408889634f * x)); }
;                 }
;                 if (TYPE == 4 || TYPE == 5) {
;                     float ss = 0.f;
; #pragma unroll
;                     for (int bj = 0; bj < 2; ++bj)
; #pragma unroll
;                         for (int j = 0; j < 8; ++j) ss += v[bj][j] * v[bj][j];
;                     ss = quad_sum(ss);
;                     const float r = rsqrtf(ss * (1.0f / 64.0f) + EPS);
; #pragma unroll
;                     for (int bj = 0; bj < 2; ++bj)
; #pragma unroll
;                         for (int j = 0; j < 8; ++j) v[bj][j] = v[bj][j] * r * g[bj][j];
;                 }
;                 bf16_t* rowp = Z + (size_t)row * DIN + colbase;
;                 *(u32x4*)(rowp) = pack8(v[0]); *(u32x4*)(rowp + 32) = pack8(v[1]);
;     __device__ __forceinline__ void operator()(const Acc& acc, const Unit& u, int wr, int wc, int fr, int fq) const {
;         const int pn = u.pn;
;         if (pn < 2) run<0>(acc, u, wr, wc, fr, fq);
;         else if (pn < 4) run<1>(acc, u, wr, wc, fr, fq);
;         else if (pn < 8) run<2>(acc, u, wr, wc, fr, fq);
;         else if (pn < 12) run<3>(acc, u, wr, wc, fr, fq);
;         else if (pn < 16) run<4>(acc, u, wr, wc, fr, fq);
;         else if (pn < 20) run<5>(acc, u, wr, wc, fr, fq);
;         else if (pn < 24) run<2>(acc, u, wr, wc, fr, fq);
;         else run<3>(acc, u, wr, wc, fr, fq);
.LBB0_108:
	v_mov_b32_e32 v253, 0
	global_load_dword v253, v253, s[88:89] offset:256 sc1
	v_mov_b32_e32 v128, v185
	s_cmp_gt_i32 s44, 1
	v_and_b32_e32 v209, 15, v128
	v_bfe_u32 v210, v128, 4, 2
	s_mov_b64 s[2:3], -1
	s_cbranch_scc0 .LBB0_302
	s_cmp_gt_u32 s44, 3
	s_cbranch_scc0 .LBB0_131
	s_cmp_gt_u32 s44, 7
	s_cbranch_scc0 .LBB0_128
	s_cmp_gt_u32 s44, 11
	s_cbranch_scc0 .LBB0_125
	s_cmp_gt_u32 s44, 15
	s_cbranch_scc0 .LBB0_122
	s_cmp_gt_u32 s44, 19
	s_cbranch_scc0 .LBB0_119
	s_lshl_b32 s2, s44, 8
	s_or_b32 s6, s2, s86
	s_cmp_gt_u32 s44, 23
	s_mov_b64 s[2:3], -1
	s_cbranch_scc0 .LBB0_116
	v_mov_b32_e32 v128, v210
	v_mov_b32_e32 v152, v209
	v_mul_f32_e32 v129, 0xbfb8aa3b, v125
	v_lshl_add_u32 v162, v128, 3, s6
	v_mul_f32_e32 v128, 0xbfb8aa3b, v124
	v_exp_f32_e32 v128, v128
	v_exp_f32_e32 v129, v129
	v_mul_f32_e32 v130, 0xbfb8aa3b, v126
	v_mul_f32_e32 v131, 0xbfb8aa3b, v127
	v_add_f32_e32 v128, 1.0, v128
	v_add_f32_e32 v129, 1.0, v129
	v_rcp_f32_e32 v128, v128
	v_rcp_f32_e32 v129, v129
	v_exp_f32_e32 v130, v130
	v_exp_f32_e32 v131, v131
	v_mul_f32_e32 v132, 0xbfb8aa3b, v112
	v_pk_mul_f32 v[134:135], v[124:125], v[128:129]
	v_add_f32_e32 v128, 1.0, v130
	v_add_f32_e32 v129, 1.0, v131
	v_mul_f32_e32 v130, 0xbfb8aa3b, v120
	v_mul_f32_e32 v131, 0xbfb8aa3b, v121
	v_rcp_f32_e32 v128, v128
	v_rcp_f32_e32 v129, v129
	v_exp_f32_e32 v130, v130
	v_exp_f32_e32 v131, v131
	v_mul_f32_e32 v133, 0xbfb8aa3b, v113
	v_pk_mul_f32 v[136:137], v[126:127], v[128:129]
	v_add_f32_e32 v128, 1.0, v130
	v_add_f32_e32 v129, 1.0, v131
	v_mul_f32_e32 v130, 0xbfb8aa3b, v122
	v_mul_f32_e32 v131, 0xbfb8aa3b, v123
	v_rcp_f32_e32 v128, v128
	v_rcp_f32_e32 v129, v129
	v_exp_f32_e32 v130, v130
	v_exp_f32_e32 v131, v131
	v_exp_f32_e32 v132, v132
	v_pk_mul_f32 v[138:139], v[120:121], v[128:129]
	v_add_f32_e32 v128, 1.0, v130
	v_add_f32_e32 v129, 1.0, v131
	v_mul_f32_e32 v130, 0xbfb8aa3b, v116
	v_mul_f32_e32 v131, 0xbfb8aa3b, v117
	v_rcp_f32_e32 v128, v128
	v_rcp_f32_e32 v129, v129
	v_exp_f32_e32 v130, v130
	v_exp_f32_e32 v131, v131
	v_exp_f32_e32 v133, v133
	v_pk_mul_f32 v[140:141], v[122:123], v[128:129]
	v_add_f32_e32 v128, 1.0, v130
	v_add_f32_e32 v129, 1.0, v131
	v_mul_f32_e32 v130, 0xbfb8aa3b, v118
	v_mul_f32_e32 v131, 0xbfb8aa3b, v119
	v_exp_f32_e32 v130, v130
	v_exp_f32_e32 v131, v131
	v_mul_f32_e32 v142, 0xbfb8aa3b, v114
	v_mul_f32_e32 v143, 0xbfb8aa3b, v115
	v_add_f32_e32 v132, 1.0, v132
	v_add_f32_e32 v133, 1.0, v133
	v_exp_f32_e32 v142, v142
	v_exp_f32_e32 v143, v143
	v_rcp_f32_e32 v132, v132
	v_rcp_f32_e32 v133, v133
	v_rcp_f32_e32 v128, v128
	v_rcp_f32_e32 v129, v129
	v_add_f32_e32 v130, 1.0, v130
	v_add_f32_e32 v131, 1.0, v131
	v_rcp_f32_e32 v130, v130
	v_rcp_f32_e32 v131, v131
	v_add_f32_e32 v142, 1.0, v142
	v_add_f32_e32 v143, 1.0, v143
	s_lshl_b32 s2, s46, 8
	v_rcp_f32_e32 v142, v142
	v_rcp_f32_e32 v143, v143
	v_pk_mul_f32 v[168:169], v[112:113], v[132:133]
	v_mul_f32_e32 v133, 0xbfb8aa3b, v108
	s_add_i32 s2, s2, s79
	v_cvt_pk_bf16_f32 v134, v134, v135
	v_cvt_pk_bf16_f32 v135, v136, v137
	v_cvt_pk_bf16_f32 v136, v138, v139
	v_exp_f32_e32 v133, v133
	v_mul_f32_e32 v138, 0xbfb8aa3b, v109
	v_ashrrev_i32_e32 v163, 31, v162
	v_pk_mul_f32 v[164:165], v[116:117], v[128:129]
	v_add_u32_e32 v132, s2, v152
	v_mov_b64_e32 v[128:129], s[22:23]
	v_exp_f32_e32 v138, v138
	v_pk_mul_f32 v[166:167], v[118:119], v[130:131]
	v_mad_i64_i32 v[170:171], s[2:3], v132, s68, v[128:129]
	v_lshlrev_b64 v[130:131], 1, v[162:163]
	v_pk_mul_f32 v[142:143], v[114:115], v[142:143]
	v_lshl_add_u64 v[170:171], v[170:171], 0, v[130:131]
	v_cvt_pk_bf16_f32 v137, v140, v141
	global_store_dwordx4 v[170:171], v[134:137], off
	v_add_f32_e32 v133, 1.0, v133
	v_mul_f32_e32 v140, 0xbfb8aa3b, v107
	v_cvt_pk_bf16_f32 v134, v164, v165
	v_cvt_pk_bf16_f32 v135, v166, v167
	v_cvt_pk_bf16_f32 v136, v168, v169
	v_cvt_pk_bf16_f32 v137, v142, v143
	global_store_dwordx4 v[170:171], v[134:137], off offset:64
	v_exp_f32_e32 v141, v140
	v_mul_f32_e32 v142, 0xbfb8aa3b, v101
	v_rcp_f32_e32 v134, v133
	v_add_f32_e32 v133, 1.0, v138
	v_rcp_f32_e32 v135, v133
	v_mul_f32_e32 v133, 0xbfb8aa3b, v110
	v_exp_f32_e32 v133, v133
	v_mul_f32_e32 v136, 0xbfb8aa3b, v111
	v_exp_f32_e32 v137, v136
	v_mul_f32_e32 v138, 0xbfb8aa3b, v105
	v_add_f32_e32 v133, 1.0, v133
	v_rcp_f32_e32 v136, v133
	v_add_f32_e32 v133, 1.0, v137
	v_rcp_f32_e32 v137, v133
	v_mul_f32_e32 v133, 0xbfb8aa3b, v104
	v_exp_f32_e32 v133, v133
	v_exp_f32_e32 v139, v138
	v_exp_f32_e32 v143, v142
	v_pk_mul_f32 v[134:135], v[108:109], v[134:135]
	v_add_f32_e32 v133, 1.0, v133
	v_rcp_f32_e32 v138, v133
	v_add_f32_e32 v133, 1.0, v139
	v_rcp_f32_e32 v139, v133
	v_mul_f32_e32 v133, 0xbfb8aa3b, v106
	v_exp_f32_e32 v133, v133
	v_pk_mul_f32 v[136:137], v[110:111], v[136:137]
	v_pk_mul_f32 v[138:139], v[104:105], v[138:139]
	v_cvt_pk_bf16_f32 v134, v134, v135
	v_add_f32_e32 v133, 1.0, v133
	v_rcp_f32_e32 v140, v133
	v_add_f32_e32 v133, 1.0, v141
	v_rcp_f32_e32 v141, v133
	v_mul_f32_e32 v133, 0xbfb8aa3b, v100
	v_exp_f32_e32 v133, v133
	v_cvt_pk_bf16_f32 v135, v136, v137
	v_cvt_pk_bf16_f32 v136, v138, v139
	v_mul_f32_e32 v138, 0xbfb8aa3b, v93
	v_add_f32_e32 v133, 1.0, v133
	v_rcp_f32_e32 v142, v133
	v_add_f32_e32 v133, 1.0, v143
	v_mul_f32_e32 v143, 0xbfb8aa3b, v102
	v_exp_f32_e32 v152, v143
	v_mul_f32_e32 v143, 0xbfb8aa3b, v103
	v_exp_f32_e32 v159, v143
	v_rcp_f32_e32 v143, v133
	v_add_f32_e32 v133, 1.0, v152
	v_mul_f32_e32 v152, 0xbfb8aa3b, v96
	v_rcp_f32_e32 v164, v133
	v_add_f32_e32 v133, 1.0, v159
	v_exp_f32_e32 v152, v152
	v_mul_f32_e32 v159, 0xbfb8aa3b, v97
	v_exp_f32_e32 v159, v159
	v_rcp_f32_e32 v165, v133
	v_add_f32_e32 v133, 1.0, v152
	v_mul_f32_e32 v152, 0xbfb8aa3b, v98
; __device__ __forceinline__ u32x4 pack8(const float (&v)[8]) { u32x4 w; w.x = cvtpk(v[0], v[1]); w.y = cvtpk(v[2], v[3]); w.z = cvtpk(v[4], v[5]); w.w = cvtpk(v[6], v[7]); return w; }
;     template <int TYPE> __device__ __forceinline__ void run(const Acc& acc, const Unit& u, int wr, int wc, int fr, int fq) const {
;     ...
;                 if (TYPE == 3) {
; #pragma unroll
;                     for (int bj = 0; bj < 2; ++bj)
; #pragma unroll
;                         for (int j = 0; j < 8; ++j) { const float x = v[bj][j]; v[bj][j] = x * __builtin_amdgcn_rcpf(1.0f + __builtin_amdgcn_exp2f(-1.4426950408889634f * x)); }
;                 }
;                 if (TYPE == 4 || TYPE == 5) {
;                     float ss = 0.f;
; #pragma unroll
;                     for (int bj = 0; bj < 2; ++bj)
; #pragma unroll
;                         for (int j = 0; j < 8; ++j) ss += v[bj][j] * v[bj][j];
;                     ss = quad_sum(ss);
;                     const float r = rsqrtf(ss * (1.0f / 64.0f) + EPS);
; #pragma unroll
;                     for (int bj = 0; bj < 2; ++bj)
; #pragma unroll
;                         for (int j = 0; j < 8; ++j) v[bj][j] = v[bj][j] * r * g[bj][j];
;                 }
;                 bf16_t* rowp = Z + (size_t)row * DIN + colbase;
;                 *(u32x4*)(rowp) = pack8(v[0]); *(u32x4*)(rowp + 32) = pack8(v[1]);
	v_rcp_f32_e32 v166, v133
	v_add_f32_e32 v133, 1.0, v159
	v_exp_f32_e32 v152, v152
	v_mul_f32_e32 v159, 0xbfb8aa3b, v99
	v_exp_f32_e32 v159, v159
	v_rcp_f32_e32 v167, v133
	v_add_f32_e32 v133, 1.0, v152
	v_rcp_f32_e32 v168, v133
	v_add_f32_e32 v133, 1.0, v159
	v_rcp_f32_e32 v169, v133
	v_add_u32_e32 v133, 16, v132
	v_mad_i64_i32 v[170:171], s[2:3], v133, s68, v[128:129]
	v_mul_f32_e32 v133, 0xbfb8aa3b, v92
	v_exp_f32_e32 v133, v133
	v_exp_f32_e32 v138, v138
	v_pk_mul_f32 v[140:141], v[106:107], v[140:141]
	v_pk_mul_f32 v[142:143], v[100:101], v[142:143]
	v_pk_mul_f32 v[164:165], v[102:103], v[164:165]
	v_pk_mul_f32 v[166:167], v[96:97], v[166:167]
	v_pk_mul_f32 v[168:169], v[98:99], v[168:169]
	v_lshl_add_u64 v[170:171], v[170:171], 0, v[130:131]
	v_cvt_pk_bf16_f32 v137, v140, v141
	global_store_dwordx4 v[170:171], v[134:137], off
	v_add_f32_e32 v133, 1.0, v133
	v_mul_f32_e32 v140, 0xbfb8aa3b, v91
	v_cvt_pk_bf16_f32 v134, v142, v143
	v_cvt_pk_bf16_f32 v135, v164, v165
	v_cvt_pk_bf16_f32 v136, v166, v167
	v_cvt_pk_bf16_f32 v137, v168, v169
	global_store_dwordx4 v[170:171], v[134:137], off offset:64
	v_exp_f32_e32 v141, v140
	v_mul_f32_e32 v142, 0xbfb8aa3b, v85
	v_rcp_f32_e32 v134, v133
	v_add_f32_e32 v133, 1.0, v138
	v_rcp_f32_e32 v135, v133
	v_mul_f32_e32 v133, 0xbfb8aa3b, v94
	v_exp_f32_e32 v133, v133
	v_mul_f32_e32 v136, 0xbfb8aa3b, v95
	v_exp_f32_e32 v137, v136
	v_mul_f32_e32 v138, 0xbfb8aa3b, v89
	v_add_f32_e32 v133, 1.0, v133
	v_rcp_f32_e32 v136, v133
	v_add_f32_e32 v133, 1.0, v137
	v_rcp_f32_e32 v137, v133
	v_mul_f32_e32 v133, 0xbfb8aa3b, v88
	v_exp_f32_e32 v133, v133
	v_exp_f32_e32 v139, v138
	v_exp_f32_e32 v143, v142
	v_pk_mul_f32 v[134:135], v[92:93], v[134:135]
	v_add_f32_e32 v133, 1.0, v133
	v_rcp_f32_e32 v138, v133
	v_add_f32_e32 v133, 1.0, v139
	v_rcp_f32_e32 v139, v133
	v_mul_f32_e32 v133, 0xbfb8aa3b, v90
	v_exp_f32_e32 v133, v133
	v_pk_mul_f32 v[136:137], v[94:95], v[136:137]
	v_pk_mul_f32 v[138:139], v[88:89], v[138:139]
	v_cvt_pk_bf16_f32 v134, v134, v135
	v_add_f32_e32 v133, 1.0, v133
	v_rcp_f32_e32 v140, v133
	v_add_f32_e32 v133, 1.0, v141
	v_rcp_f32_e32 v141, v133
	v_mul_f32_e32 v133, 0xbfb8aa3b, v84
	v_exp_f32_e32 v133, v133
	v_cvt_pk_bf16_f32 v135, v136, v137
	v_cvt_pk_bf16_f32 v136, v138, v139
	v_mul_f32_e32 v138, 0xbfb8aa3b, v77
	v_add_f32_e32 v133, 1.0, v133
	v_rcp_f32_e32 v142, v133
	v_add_f32_e32 v133, 1.0, v143
	v_mul_f32_e32 v143, 0xbfb8aa3b, v86
	v_exp_f32_e32 v152, v143
	v_mul_f32_e32 v143, 0xbfb8aa3b, v87
	v_exp_f32_e32 v159, v143
	v_rcp_f32_e32 v143, v133
	v_add_f32_e32 v133, 1.0, v152
	v_mul_f32_e32 v152, 0xbfb8aa3b, v80
	v_rcp_f32_e32 v164, v133
	v_add_f32_e32 v133, 1.0, v159
	v_exp_f32_e32 v152, v152
	v_mul_f32_e32 v159, 0xbfb8aa3b, v81
	v_exp_f32_e32 v159, v159
	v_rcp_f32_e32 v165, v133
	v_add_f32_e32 v133, 1.0, v152
	v_mul_f32_e32 v152, 0xbfb8aa3b, v82
	v_rcp_f32_e32 v166, v133
	v_add_f32_e32 v133, 1.0, v159
	v_exp_f32_e32 v152, v152
	v_mul_f32_e32 v159, 0xbfb8aa3b, v83
	v_exp_f32_e32 v159, v159
	v_rcp_f32_e32 v167, v133
	v_add_f32_e32 v133, 1.0, v152
	v_rcp_f32_e32 v168, v133
	v_add_f32_e32 v133, 1.0, v159
	v_rcp_f32_e32 v169, v133
	v_add_u32_e32 v133, 32, v132
	v_mad_i64_i32 v[170:171], s[2:3], v133, s68, v[128:129]
	v_mul_f32_e32 v133, 0xbfb8aa3b, v76
	v_exp_f32_e32 v133, v133
	v_exp_f32_e32 v138, v138
	v_pk_mul_f32 v[140:141], v[90:91], v[140:141]
	v_pk_mul_f32 v[142:143], v[84:85], v[142:143]
	v_pk_mul_f32 v[164:165], v[86:87], v[164:165]
	v_pk_mul_f32 v[166:167], v[80:81], v[166:167]
	v_pk_mul_f32 v[168:169], v[82:83], v[168:169]
	v_lshl_add_u64 v[170:171], v[170:171], 0, v[130:131]
	v_cvt_pk_bf16_f32 v137, v140, v141
	global_store_dwordx4 v[170:171], v[134:137], off
	v_add_f32_e32 v133, 1.0, v133
	v_mul_f32_e32 v140, 0xbfb8aa3b, v75
	v_cvt_pk_bf16_f32 v134, v142, v143
	v_cvt_pk_bf16_f32 v135, v164, v165
	v_cvt_pk_bf16_f32 v136, v166, v167
	v_cvt_pk_bf16_f32 v137, v168, v169
	global_store_dwordx4 v[170:171], v[134:137], off offset:64
	v_exp_f32_e32 v141, v140
	v_mul_f32_e32 v142, 0xbfb8aa3b, v69
	v_rcp_f32_e32 v134, v133
	v_add_f32_e32 v133, 1.0, v138
	v_rcp_f32_e32 v135, v133
	v_mul_f32_e32 v133, 0xbfb8aa3b, v78
	v_exp_f32_e32 v133, v133
	v_mul_f32_e32 v136, 0xbfb8aa3b, v79
	v_exp_f32_e32 v137, v136
	v_mul_f32_e32 v138, 0xbfb8aa3b, v73
	v_add_f32_e32 v133, 1.0, v133
	v_rcp_f32_e32 v136, v133
	v_add_f32_e32 v133, 1.0, v137
	v_rcp_f32_e32 v137, v133
	v_mul_f32_e32 v133, 0xbfb8aa3b, v72
	v_exp_f32_e32 v133, v133
	v_exp_f32_e32 v139, v138
	v_exp_f32_e32 v143, v142
	v_pk_mul_f32 v[134:135], v[76:77], v[134:135]
	v_add_f32_e32 v133, 1.0, v133
	v_rcp_f32_e32 v138, v133
	v_add_f32_e32 v133, 1.0, v139
	v_rcp_f32_e32 v139, v133
	v_mul_f32_e32 v133, 0xbfb8aa3b, v74
	v_exp_f32_e32 v133, v133
	v_pk_mul_f32 v[136:137], v[78:79], v[136:137]
	v_pk_mul_f32 v[138:139], v[72:73], v[138:139]
	v_cvt_pk_bf16_f32 v134, v134, v135
	v_add_f32_e32 v133, 1.0, v133
	v_rcp_f32_e32 v140, v133
	v_add_f32_e32 v133, 1.0, v141
	v_rcp_f32_e32 v141, v133
	v_mul_f32_e32 v133, 0xbfb8aa3b, v68
	v_exp_f32_e32 v133, v133
	v_cvt_pk_bf16_f32 v135, v136, v137
	v_cvt_pk_bf16_f32 v136, v138, v139
	v_mul_f32_e32 v138, 0xbfb8aa3b, v61
	v_add_f32_e32 v133, 1.0, v133
	v_rcp_f32_e32 v142, v133
	v_add_f32_e32 v133, 1.0, v143
	v_mul_f32_e32 v143, 0xbfb8aa3b, v70
	v_exp_f32_e32 v152, v143
	v_mul_f32_e32 v143, 0xbfb8aa3b, v71
	v_exp_f32_e32 v159, v143
	v_rcp_f32_e32 v143, v133
	v_add_f32_e32 v133, 1.0, v152
	v_mul_f32_e32 v152, 0xbfb8aa3b, v64
	v_rcp_f32_e32 v164, v133
	v_add_f32_e32 v133, 1.0, v159
	v_exp_f32_e32 v152, v152
	v_mul_f32_e32 v159, 0xbfb8aa3b, v65
	v_exp_f32_e32 v159, v159
	v_rcp_f32_e32 v165, v133
	v_add_f32_e32 v133, 1.0, v152
; __device__ __forceinline__ u32x4 pack8(const float (&v)[8]) { u32x4 w; w.x = cvtpk(v[0], v[1]); w.y = cvtpk(v[2], v[3]); w.z = cvtpk(v[4], v[5]); w.w = cvtpk(v[6], v[7]); return w; }
;     template <int TYPE> __device__ __forceinline__ void run(const Acc& acc, const Unit& u, int wr, int wc, int fr, int fq) const {
;     ...
;                 if (TYPE == 3) {
; #pragma unroll
;                     for (int bj = 0; bj < 2; ++bj)
; #pragma unroll
;                         for (int j = 0; j < 8; ++j) { const float x = v[bj][j]; v[bj][j] = x * __builtin_amdgcn_rcpf(1.0f + __builtin_amdgcn_exp2f(-1.4426950408889634f * x)); }
;                 }
;                 if (TYPE == 4 || TYPE == 5) {
;                     float ss = 0.f;
; #pragma unroll
;                     for (int bj = 0; bj < 2; ++bj)
; #pragma unroll
;                         for (int j = 0; j < 8; ++j) ss += v[bj][j] * v[bj][j];
;                     ss = quad_sum(ss);
;                     const float r = rsqrtf(ss * (1.0f / 64.0f) + EPS);
; #pragma unroll
;                     for (int bj = 0; bj < 2; ++bj)
; #pragma unroll
;                         for (int j = 0; j < 8; ++j) v[bj][j] = v[bj][j] * r * g[bj][j];
;                 }
;                 bf16_t* rowp = Z + (size_t)row * DIN + colbase;
;                 *(u32x4*)(rowp) = pack8(v[0]); *(u32x4*)(rowp + 32) = pack8(v[1]);
	v_mul_f32_e32 v152, 0xbfb8aa3b, v66
	v_rcp_f32_e32 v166, v133
	v_add_f32_e32 v133, 1.0, v159
	v_exp_f32_e32 v152, v152
	v_mul_f32_e32 v159, 0xbfb8aa3b, v67
	v_exp_f32_e32 v159, v159
	v_rcp_f32_e32 v167, v133
	v_add_f32_e32 v133, 1.0, v152
	v_rcp_f32_e32 v168, v133
	v_add_f32_e32 v133, 1.0, v159
	v_rcp_f32_e32 v169, v133
	v_add_u32_e32 v133, 48, v132
	v_mad_i64_i32 v[170:171], s[2:3], v133, s68, v[128:129]
	v_mul_f32_e32 v133, 0xbfb8aa3b, v60
	v_exp_f32_e32 v133, v133
	v_exp_f32_e32 v138, v138
	v_pk_mul_f32 v[140:141], v[74:75], v[140:141]
	v_pk_mul_f32 v[142:143], v[68:69], v[142:143]
	v_pk_mul_f32 v[164:165], v[70:71], v[164:165]
	v_pk_mul_f32 v[166:167], v[64:65], v[166:167]
	v_pk_mul_f32 v[168:169], v[66:67], v[168:169]
	v_lshl_add_u64 v[170:171], v[170:171], 0, v[130:131]
	v_cvt_pk_bf16_f32 v137, v140, v141
	global_store_dwordx4 v[170:171], v[134:137], off
	v_add_f32_e32 v133, 1.0, v133
	v_mul_f32_e32 v140, 0xbfb8aa3b, v59
	v_cvt_pk_bf16_f32 v134, v142, v143
	v_cvt_pk_bf16_f32 v135, v164, v165
	v_cvt_pk_bf16_f32 v136, v166, v167
	v_cvt_pk_bf16_f32 v137, v168, v169
	global_store_dwordx4 v[170:171], v[134:137], off offset:64
	v_exp_f32_e32 v141, v140
	v_mul_f32_e32 v142, 0xbfb8aa3b, v53
	v_rcp_f32_e32 v134, v133
	v_add_f32_e32 v133, 1.0, v138
	v_rcp_f32_e32 v135, v133
	v_mul_f32_e32 v133, 0xbfb8aa3b, v62
	v_exp_f32_e32 v133, v133
	v_mul_f32_e32 v136, 0xbfb8aa3b, v63
	v_exp_f32_e32 v137, v136
	v_mul_f32_e32 v138, 0xbfb8aa3b, v57
	v_add_f32_e32 v133, 1.0, v133
	v_rcp_f32_e32 v136, v133
	v_add_f32_e32 v133, 1.0, v137
	v_rcp_f32_e32 v137, v133
	v_mul_f32_e32 v133, 0xbfb8aa3b, v56
	v_exp_f32_e32 v133, v133
	v_exp_f32_e32 v139, v138
	v_exp_f32_e32 v143, v142
	v_pk_mul_f32 v[134:135], v[60:61], v[134:135]
	v_add_f32_e32 v133, 1.0, v133
	v_rcp_f32_e32 v138, v133
	v_add_f32_e32 v133, 1.0, v139
	v_rcp_f32_e32 v139, v133
	v_mul_f32_e32 v133, 0xbfb8aa3b, v58
	v_exp_f32_e32 v133, v133
	v_pk_mul_f32 v[136:137], v[62:63], v[136:137]
	v_pk_mul_f32 v[138:139], v[56:57], v[138:139]
	v_cvt_pk_bf16_f32 v134, v134, v135
	v_add_f32_e32 v133, 1.0, v133
	v_rcp_f32_e32 v140, v133
	v_add_f32_e32 v133, 1.0, v141
	v_rcp_f32_e32 v141, v133
	v_mul_f32_e32 v133, 0xbfb8aa3b, v52
	v_exp_f32_e32 v133, v133
	v_cvt_pk_bf16_f32 v135, v136, v137
	v_cvt_pk_bf16_f32 v136, v138, v139
	v_mul_f32_e32 v138, 0xbfb8aa3b, v45
	v_add_f32_e32 v133, 1.0, v133
	v_rcp_f32_e32 v142, v133
	v_add_f32_e32 v133, 1.0, v143
	v_mul_f32_e32 v143, 0xbfb8aa3b, v54
	v_exp_f32_e32 v152, v143
	v_mul_f32_e32 v143, 0xbfb8aa3b, v55
	v_exp_f32_e32 v159, v143
	v_rcp_f32_e32 v143, v133
	v_add_f32_e32 v133, 1.0, v152
	v_mul_f32_e32 v152, 0xbfb8aa3b, v48
	v_rcp_f32_e32 v164, v133
	v_add_f32_e32 v133, 1.0, v159
	v_exp_f32_e32 v152, v152
	v_mul_f32_e32 v159, 0xbfb8aa3b, v49
	v_exp_f32_e32 v159, v159
	v_rcp_f32_e32 v165, v133
	v_add_f32_e32 v133, 1.0, v152
	v_mul_f32_e32 v152, 0xbfb8aa3b, v50
	v_rcp_f32_e32 v166, v133
	v_add_f32_e32 v133, 1.0, v159
	v_exp_f32_e32 v152, v152
	v_mul_f32_e32 v159, 0xbfb8aa3b, v51
	v_exp_f32_e32 v159, v159
	v_rcp_f32_e32 v167, v133
	v_add_f32_e32 v133, 1.0, v152
	v_rcp_f32_e32 v168, v133
	v_add_f32_e32 v133, 1.0, v159
	v_rcp_f32_e32 v169, v133
	v_add_u32_e32 v133, 0x80, v132
	v_mad_i64_i32 v[170:171], s[2:3], v133, s68, v[128:129]
	v_mul_f32_e32 v133, 0xbfb8aa3b, v44
	v_exp_f32_e32 v133, v133
	v_exp_f32_e32 v138, v138
	v_pk_mul_f32 v[140:141], v[58:59], v[140:141]
	v_pk_mul_f32 v[142:143], v[52:53], v[142:143]
	v_pk_mul_f32 v[164:165], v[54:55], v[164:165]
	v_pk_mul_f32 v[166:167], v[48:49], v[166:167]
	v_pk_mul_f32 v[168:169], v[50:51], v[168:169]
	v_lshl_add_u64 v[170:171], v[170:171], 0, v[130:131]
	v_cvt_pk_bf16_f32 v137, v140, v141
	global_store_dwordx4 v[170:171], v[134:137], off
	v_add_f32_e32 v133, 1.0, v133
	v_mul_f32_e32 v140, 0xbfb8aa3b, v43
	v_cvt_pk_bf16_f32 v134, v142, v143
	v_cvt_pk_bf16_f32 v135, v164, v165
	v_cvt_pk_bf16_f32 v136, v166, v167
	v_cvt_pk_bf16_f32 v137, v168, v169
	global_store_dwordx4 v[170:171], v[134:137], off offset:64
	v_exp_f32_e32 v141, v140
	v_mul_f32_e32 v142, 0xbfb8aa3b, v37
	v_rcp_f32_e32 v134, v133
	v_add_f32_e32 v133, 1.0, v138
	v_rcp_f32_e32 v135, v133
	v_mul_f32_e32 v133, 0xbfb8aa3b, v46
	v_exp_f32_e32 v133, v133
	v_mul_f32_e32 v136, 0xbfb8aa3b, v47
	v_exp_f32_e32 v137, v136
	v_mul_f32_e32 v138, 0xbfb8aa3b, v41
	v_add_f32_e32 v133, 1.0, v133
	v_rcp_f32_e32 v136, v133
	v_add_f32_e32 v133, 1.0, v137
	v_rcp_f32_e32 v137, v133
	v_mul_f32_e32 v133, 0xbfb8aa3b, v40
	v_exp_f32_e32 v133, v133
	v_exp_f32_e32 v139, v138
	v_exp_f32_e32 v143, v142
	v_pk_mul_f32 v[134:135], v[44:45], v[134:135]
	v_add_f32_e32 v133, 1.0, v133
	v_rcp_f32_e32 v138, v133
	v_add_f32_e32 v133, 1.0, v139
	v_rcp_f32_e32 v139, v133
	v_mul_f32_e32 v133, 0xbfb8aa3b, v42
	v_exp_f32_e32 v133, v133
	v_pk_mul_f32 v[136:137], v[46:47], v[136:137]
	v_pk_mul_f32 v[138:139], v[40:41], v[138:139]
	v_cvt_pk_bf16_f32 v134, v134, v135
	v_add_f32_e32 v133, 1.0, v133
	v_rcp_f32_e32 v140, v133
	v_add_f32_e32 v133, 1.0, v141
	v_rcp_f32_e32 v141, v133
	v_mul_f32_e32 v133, 0xbfb8aa3b, v36
	v_exp_f32_e32 v133, v133
	v_cvt_pk_bf16_f32 v135, v136, v137
	v_cvt_pk_bf16_f32 v136, v138, v139
	v_mul_f32_e32 v138, 0xbfb8aa3b, v29
	v_add_f32_e32 v133, 1.0, v133
	v_rcp_f32_e32 v142, v133
	v_add_f32_e32 v133, 1.0, v143
	v_mul_f32_e32 v143, 0xbfb8aa3b, v38
	v_exp_f32_e32 v152, v143
	v_mul_f32_e32 v143, 0xbfb8aa3b, v39
	v_exp_f32_e32 v159, v143
	v_rcp_f32_e32 v143, v133
	v_add_f32_e32 v133, 1.0, v152
	v_mul_f32_e32 v152, 0xbfb8aa3b, v32
	v_rcp_f32_e32 v164, v133
	v_add_f32_e32 v133, 1.0, v159
	v_exp_f32_e32 v152, v152
	v_mul_f32_e32 v159, 0xbfb8aa3b, v33
	v_exp_f32_e32 v159, v159
	v_rcp_f32_e32 v165, v133
; __device__ __forceinline__ u32x4 pack8(const float (&v)[8]) { u32x4 w; w.x = cvtpk(v[0], v[1]); w.y = cvtpk(v[2], v[3]); w.z = cvtpk(v[4], v[5]); w.w = cvtpk(v[6], v[7]); return w; }
;     template <int TYPE> __device__ __forceinline__ void run(const Acc& acc, const Unit& u, int wr, int wc, int fr, int fq) const {
;     ...
;                 if (TYPE == 3) {
; #pragma unroll
;                     for (int bj = 0; bj < 2; ++bj)
; #pragma unroll
;                         for (int j = 0; j < 8; ++j) { const float x = v[bj][j]; v[bj][j] = x * __builtin_amdgcn_rcpf(1.0f + __builtin_amdgcn_exp2f(-1.4426950408889634f * x)); }
;                 }
;                 if (TYPE == 4 || TYPE == 5) {
;                     float ss = 0.f;
; #pragma unroll
;                     for (int bj = 0; bj < 2; ++bj)
; #pragma unroll
;                         for (int j = 0; j < 8; ++j) ss += v[bj][j] * v[bj][j];
;                     ss = quad_sum(ss);
;                     const float r = rsqrtf(ss * (1.0f / 64.0f) + EPS);
; #pragma unroll
;                     for (int bj = 0; bj < 2; ++bj)
; #pragma unroll
;                         for (int j = 0; j < 8; ++j) v[bj][j] = v[bj][j] * r * g[bj][j];
;                 }
;                 bf16_t* rowp = Z + (size_t)row * DIN + colbase;
;                 *(u32x4*)(rowp) = pack8(v[0]); *(u32x4*)(rowp + 32) = pack8(v[1]);
	v_add_f32_e32 v133, 1.0, v152
	v_mul_f32_e32 v152, 0xbfb8aa3b, v34
	v_rcp_f32_e32 v166, v133
	v_add_f32_e32 v133, 1.0, v159
	v_exp_f32_e32 v152, v152
	v_mul_f32_e32 v159, 0xbfb8aa3b, v35
	v_exp_f32_e32 v159, v159
	v_rcp_f32_e32 v167, v133
	v_add_f32_e32 v133, 1.0, v152
	v_rcp_f32_e32 v168, v133
	v_add_f32_e32 v133, 1.0, v159
	v_rcp_f32_e32 v169, v133
	v_add_u32_e32 v133, 0x90, v132
	v_mad_i64_i32 v[170:171], s[2:3], v133, s68, v[128:129]
	v_mul_f32_e32 v133, 0xbfb8aa3b, v28
	v_exp_f32_e32 v133, v133
	v_exp_f32_e32 v138, v138
	v_pk_mul_f32 v[140:141], v[42:43], v[140:141]
	v_pk_mul_f32 v[142:143], v[36:37], v[142:143]
	v_pk_mul_f32 v[164:165], v[38:39], v[164:165]
	v_pk_mul_f32 v[166:167], v[32:33], v[166:167]
	v_pk_mul_f32 v[168:169], v[34:35], v[168:169]
	v_lshl_add_u64 v[170:171], v[170:171], 0, v[130:131]
	v_cvt_pk_bf16_f32 v137, v140, v141
	global_store_dwordx4 v[170:171], v[134:137], off
	v_add_f32_e32 v133, 1.0, v133
	v_mul_f32_e32 v140, 0xbfb8aa3b, v27
	v_cvt_pk_bf16_f32 v134, v142, v143
	v_cvt_pk_bf16_f32 v135, v164, v165
	v_cvt_pk_bf16_f32 v136, v166, v167
	v_cvt_pk_bf16_f32 v137, v168, v169
	global_store_dwordx4 v[170:171], v[134:137], off offset:64
	v_exp_f32_e32 v141, v140
	v_mul_f32_e32 v142, 0xbfb8aa3b, v21
	v_rcp_f32_e32 v134, v133
	v_add_f32_e32 v133, 1.0, v138
	v_rcp_f32_e32 v135, v133
	v_mul_f32_e32 v133, 0xbfb8aa3b, v30
	v_exp_f32_e32 v133, v133
	v_mul_f32_e32 v136, 0xbfb8aa3b, v31
	v_exp_f32_e32 v137, v136
	v_mul_f32_e32 v138, 0xbfb8aa3b, v25
	v_add_f32_e32 v133, 1.0, v133
	v_rcp_f32_e32 v136, v133
	v_add_f32_e32 v133, 1.0, v137
	v_rcp_f32_e32 v137, v133
	v_mul_f32_e32 v133, 0xbfb8aa3b, v24
	v_exp_f32_e32 v133, v133
	v_exp_f32_e32 v139, v138
	v_exp_f32_e32 v143, v142
	v_pk_mul_f32 v[134:135], v[28:29], v[134:135]
	v_add_f32_e32 v133, 1.0, v133
	v_rcp_f32_e32 v138, v133
	v_add_f32_e32 v133, 1.0, v139
	v_rcp_f32_e32 v139, v133
	v_mul_f32_e32 v133, 0xbfb8aa3b, v26
	v_exp_f32_e32 v133, v133
	v_pk_mul_f32 v[136:137], v[30:31], v[136:137]
	v_pk_mul_f32 v[138:139], v[24:25], v[138:139]
	v_add_f32_e32 v133, 1.0, v133
	v_rcp_f32_e32 v140, v133
	v_add_f32_e32 v133, 1.0, v141
	v_rcp_f32_e32 v141, v133
	v_mul_f32_e32 v133, 0xbfb8aa3b, v20
	v_exp_f32_e32 v133, v133
	v_pk_mul_f32 v[140:141], v[26:27], v[140:141]
	v_add_f32_e32 v133, 1.0, v133
	v_rcp_f32_e32 v142, v133
	v_add_f32_e32 v133, 1.0, v143
	v_mul_f32_e32 v143, 0xbfb8aa3b, v22
	v_exp_f32_e32 v152, v143
	v_mul_f32_e32 v143, 0xbfb8aa3b, v23
	v_exp_f32_e32 v159, v143
	v_rcp_f32_e32 v143, v133
	v_add_f32_e32 v133, 1.0, v152
	v_mul_f32_e32 v152, 0xbfb8aa3b, v16
	v_rcp_f32_e32 v164, v133
	v_add_f32_e32 v133, 1.0, v159
	v_exp_f32_e32 v152, v152
	v_mul_f32_e32 v159, 0xbfb8aa3b, v17
	v_exp_f32_e32 v159, v159
	v_rcp_f32_e32 v165, v133
	v_add_f32_e32 v133, 1.0, v152
	v_mul_f32_e32 v152, 0xbfb8aa3b, v18
	v_rcp_f32_e32 v166, v133
	v_add_f32_e32 v133, 1.0, v159
	v_exp_f32_e32 v152, v152
	v_mul_f32_e32 v159, 0xbfb8aa3b, v19
	v_exp_f32_e32 v159, v159
	v_rcp_f32_e32 v167, v133
	v_add_f32_e32 v133, 1.0, v152
	v_rcp_f32_e32 v168, v133
	v_add_f32_e32 v133, 1.0, v159
	v_rcp_f32_e32 v169, v133
	v_add_u32_e32 v133, 0xa0, v132
	v_mad_i64_i32 v[128:129], s[2:3], v133, s68, v[128:129]
	v_lshl_add_u64 v[170:171], v[128:129], 0, v[130:131]
	v_cvt_pk_bf16_f32 v128, v134, v135
	v_mul_f32_e32 v133, 0xbfb8aa3b, v12
	v_mul_f32_e32 v134, 0xbfb8aa3b, v13
	v_exp_f32_e32 v133, v133
	v_exp_f32_e32 v134, v134
	v_pk_mul_f32 v[142:143], v[20:21], v[142:143]
	v_pk_mul_f32 v[164:165], v[22:23], v[164:165]
	v_pk_mul_f32 v[166:167], v[16:17], v[166:167]
	v_pk_mul_f32 v[168:169], v[18:19], v[168:169]
	v_cvt_pk_bf16_f32 v129, v136, v137
	v_cvt_pk_bf16_f32 v130, v138, v139
	v_cvt_pk_bf16_f32 v131, v140, v141
	global_store_dwordx4 v[170:171], v[128:131], off
	v_add_u32_e32 v132, 0xb0, v132
	s_mov_b64 s[2:3], 0
	v_cvt_pk_bf16_f32 v128, v142, v143
	v_cvt_pk_bf16_f32 v129, v164, v165
	v_cvt_pk_bf16_f32 v130, v166, v167
	v_cvt_pk_bf16_f32 v131, v168, v169
	global_store_dwordx4 v[170:171], v[128:131], off offset:64
	s_nop 1
	v_add_f32_e32 v128, 1.0, v133
	v_add_f32_e32 v129, 1.0, v134
	v_mul_f32_e32 v130, 0xbfb8aa3b, v14
	v_mul_f32_e32 v131, 0xbfb8aa3b, v15
	v_rcp_f32_e32 v128, v128
	v_rcp_f32_e32 v129, v129
	v_exp_f32_e32 v130, v130
	v_exp_f32_e32 v131, v131
	v_mul_f32_e32 v133, 0xbfb8aa3b, v0
	v_pk_mul_f32 v[164:165], v[12:13], v[128:129]
	v_add_f32_e32 v128, 1.0, v130
	v_add_f32_e32 v129, 1.0, v131
	v_mul_f32_e32 v130, 0xbfb8aa3b, v8
	v_mul_f32_e32 v131, 0xbfb8aa3b, v9
	v_rcp_f32_e32 v128, v128
	v_rcp_f32_e32 v129, v129
	v_exp_f32_e32 v130, v130
	v_exp_f32_e32 v131, v131
	v_exp_f32_e32 v133, v133
	v_pk_mul_f32 v[166:167], v[14:15], v[128:129]
	v_add_f32_e32 v128, 1.0, v130
	v_add_f32_e32 v129, 1.0, v131
	v_mul_f32_e32 v130, 0xbfb8aa3b, v10
	v_mul_f32_e32 v131, 0xbfb8aa3b, v11
	v_rcp_f32_e32 v128, v128
	v_rcp_f32_e32 v129, v129
	v_exp_f32_e32 v130, v130
	v_exp_f32_e32 v131, v131
	v_mul_f32_e32 v134, 0xbfb8aa3b, v1
	v_pk_mul_f32 v[168:169], v[8:9], v[128:129]
	v_add_f32_e32 v128, 1.0, v130
	v_add_f32_e32 v129, 1.0, v131
	v_mul_f32_e32 v130, 0xbfb8aa3b, v4
	v_mul_f32_e32 v131, 0xbfb8aa3b, v5
	v_exp_f32_e32 v135, v134
	v_rcp_f32_e32 v128, v128
	v_rcp_f32_e32 v129, v129
	v_exp_f32_e32 v130, v130
	v_exp_f32_e32 v131, v131
	v_add_f32_e32 v133, 1.0, v133
	v_rcp_f32_e32 v134, v133
	v_add_f32_e32 v133, 1.0, v135
	v_mul_f32_e32 v135, 0xbfb8aa3b, v2
	v_pk_mul_f32 v[170:171], v[10:11], v[128:129]
	v_add_f32_e32 v128, 1.0, v130
	v_add_f32_e32 v129, 1.0, v131
	v_mul_f32_e32 v130, 0xbfb8aa3b, v6
	v_mul_f32_e32 v131, 0xbfb8aa3b, v7
	v_exp_f32_e32 v136, v135
	v_mul_f32_e32 v135, 0xbfb8aa3b, v3
	v_exp_f32_e32 v130, v130
	v_exp_f32_e32 v131, v131
	v_exp_f32_e32 v137, v135
	v_rcp_f32_e32 v135, v133
	v_add_f32_e32 v133, 1.0, v136
	v_add_f32_e32 v130, 1.0, v130
	v_add_f32_e32 v131, 1.0, v131
	v_rcp_f32_e32 v140, v133
	v_add_f32_e32 v133, 1.0, v137
	v_rcp_f32_e32 v128, v128
	v_rcp_f32_e32 v129, v129
	v_rcp_f32_e32 v130, v130
	v_rcp_f32_e32 v131, v131
	v_rcp_f32_e32 v141, v133
	v_pk_mul_f32 v[136:137], v[4:5], v[128:129]
	v_pk_mul_f32 v[128:129], v[0:1], v[134:135]
	v_pk_mul_f32 v[138:139], v[6:7], v[130:131]
	v_pk_mul_f32 v[130:131], v[2:3], v[140:141]
